# merge-GEMM (k7) three 128x128 K-loops software-pipelined: fragment double buffer in borrowed constant registers, restored at phase end
# speedup vs baseline: 1.0116x; 1.0116x over previous
.Lxk_222:
	ds_read_b128 v[194:197], v146
	ds_read_b128 v[198:201], v146 offset:2048
	ds_read_b128 v[202:205], v146 offset:4096
	ds_read_b128 v[206:209], v146 offset:6144
	ds_read_b128 v[210:213], v147 offset:16384
	ds_read_b128 v[214:217], v147 offset:18432
	ds_read_b128 v[244:247], v147 offset:20480
	ds_read_b128 v[248:251], v147 offset:22528
	s_waitcnt lgkmcnt(8)
	v_mfma_f32_16x16x32_bf16 v[124:127], v[164:167], v[148:151], v[124:127]
	s_add_i32 s7, s7, 2
	v_mfma_f32_16x16x32_bf16 v[120:123], v[168:171], v[148:151], v[120:123]
	s_min_u32 s18, s7, 12
	v_mfma_f32_16x16x32_bf16 v[116:119], v[172:175], v[148:151], v[116:119]
	s_lshl_b32 s56, s18, 7
	v_mfma_f32_16x16x32_bf16 v[112:115], v[178:181], v[148:151], v[112:115]
	s_min_u32 s18, s7, 11
	s_waitcnt vmcnt(15)
	v_mfma_f32_16x16x32_bf16 v[108:111], v[164:167], v[152:155], v[108:111]
	ds_write_b128 v143, v[0:3] offset:32768
	v_mfma_f32_16x16x32_bf16 v[104:107], v[168:171], v[152:155], v[104:107]
	s_waitcnt vmcnt(14)
	v_mfma_f32_16x16x32_bf16 v[100:103], v[172:175], v[152:155], v[100:103]
	ds_write_b128 v143, v[4:7] offset:49152
	v_mfma_f32_16x16x32_bf16 v[96:99], v[178:181], v[152:155], v[96:99]
	s_waitcnt vmcnt(13)
	ds_write_b128 v143, v[8:11] offset:36864
	v_mfma_f32_16x16x32_bf16 v[88:91], v[164:167], v[156:159], v[88:91]
	s_waitcnt vmcnt(12)
	v_mfma_f32_16x16x32_bf16 v[84:87], v[168:171], v[156:159], v[84:87]
	ds_write_b128 v143, v[12:15] offset:53248
	v_mfma_f32_16x16x32_bf16 v[72:75], v[172:175], v[156:159], v[72:75]
	s_waitcnt vmcnt(11)
	v_mfma_f32_16x16x32_bf16 v[64:67], v[178:181], v[156:159], v[64:67]
	ds_write_b128 v143, v[16:19] offset:40960
	s_waitcnt vmcnt(10)
	v_mfma_f32_16x16x32_bf16 v[52:55], v[164:167], v[160:163], v[52:55]
	ds_write_b128 v143, v[20:23] offset:57344
	v_mfma_f32_16x16x32_bf16 v[40:43], v[168:171], v[160:163], v[40:43]
	s_waitcnt vmcnt(9)
	v_mfma_f32_16x16x32_bf16 v[36:39], v[172:175], v[160:163], v[36:39]
	ds_write_b128 v143, v[28:31] offset:45056
	v_mfma_f32_16x16x32_bf16 v[24:27], v[178:181], v[160:163], v[24:27]
	s_waitcnt vmcnt(8)
	ds_write_b128 v143, v[32:35] offset:61440
	s_waitcnt lgkmcnt(0)
	s_barrier
	ds_read_b128 v[148:151], v144 offset:32768
	ds_read_b128 v[152:155], v144 offset:34816
	ds_read_b128 v[156:159], v144 offset:36864
	ds_read_b128 v[160:163], v144 offset:38912
	ds_read_b128 v[164:167], v145 offset:49152
	ds_read_b128 v[168:171], v145 offset:51200
	ds_read_b128 v[172:175], v145 offset:53248
	ds_read_b128 v[178:181], v145 offset:55296
	v_mfma_f32_16x16x32_bf16 v[124:127], v[210:213], v[194:197], v[124:127]
	v_lshl_add_u64 v[28:29], v[138:139], 0, s[56:57]
	v_mfma_f32_16x16x32_bf16 v[120:123], v[214:217], v[194:197], v[120:123]
	v_add_co_u32_e32 v8, vcc, s65, v28
	v_lshl_add_u64 v[32:33], v[140:141], 0, s[56:57]
	v_mfma_f32_16x16x32_bf16 v[116:119], v[244:247], v[194:197], v[116:119]
	s_nop 0
	v_mfma_f32_16x16x32_bf16 v[112:115], v[248:251], v[194:197], v[112:115]
	v_addc_co_u32_e32 v9, vcc, 0, v29, vcc
	v_add_co_u32_e32 v12, vcc, s65, v32
	v_mfma_f32_16x16x32_bf16 v[108:111], v[210:213], v[198:201], v[108:111]
	global_load_dwordx4 v[0:3], v[28:29], off offset:384
	v_mfma_f32_16x16x32_bf16 v[104:107], v[214:217], v[198:201], v[104:107]
	global_load_dwordx4 v[4:7], v[32:33], off offset:384
	v_addc_co_u32_e32 v13, vcc, 0, v33, vcc
	v_mfma_f32_16x16x32_bf16 v[100:103], v[244:247], v[198:201], v[100:103]
	v_add_co_u32_e32 v16, vcc, s46, v28
	v_mfma_f32_16x16x32_bf16 v[96:99], v[248:251], v[198:201], v[96:99]
	s_nop 0
	v_addc_co_u32_e32 v17, vcc, 0, v29, vcc
	v_add_co_u32_e32 v20, vcc, s46, v32
	v_mfma_f32_16x16x32_bf16 v[88:91], v[210:213], v[202:205], v[88:91]
	s_nop 0
	v_addc_co_u32_e32 v21, vcc, 0, v33, vcc
	v_add_co_u32_e32 v28, vcc, s47, v28
	v_mfma_f32_16x16x32_bf16 v[84:87], v[214:217], v[202:205], v[84:87]
	s_nop 0
	v_addc_co_u32_e32 v29, vcc, 0, v29, vcc
	v_mfma_f32_16x16x32_bf16 v[72:75], v[244:247], v[202:205], v[72:75]
	v_add_co_u32_e32 v32, vcc, s47, v32
	s_nop 1
	v_addc_co_u32_e32 v33, vcc, 0, v33, vcc
	v_mfma_f32_16x16x32_bf16 v[64:67], v[248:251], v[202:205], v[64:67]
	global_load_dwordx4 v[8:11], v[8:9], off offset:384
	v_mfma_f32_16x16x32_bf16 v[52:55], v[210:213], v[206:209], v[52:55]
	global_load_dwordx4 v[12:15], v[12:13], off offset:384
	s_lshl_b32 s56, s18, 7
	v_mfma_f32_16x16x32_bf16 v[40:43], v[214:217], v[206:209], v[40:43]
	global_load_dwordx4 v[16:19], v[16:17], off offset:384
	v_mfma_f32_16x16x32_bf16 v[36:39], v[244:247], v[206:209], v[36:39]
	global_load_dwordx4 v[20:23], v[20:21], off offset:384
	s_cmp_lt_u32 s7, 14
	v_mfma_f32_16x16x32_bf16 v[24:27], v[248:251], v[206:209], v[24:27]
	global_load_dwordx4 v[28:31], v[28:29], off offset:384
	global_load_dwordx4 v[32:35], v[32:33], off offset:384
	ds_read_b128 v[194:197], v146 offset:32768
	ds_read_b128 v[198:201], v146 offset:34816
	ds_read_b128 v[202:205], v146 offset:36864
	ds_read_b128 v[206:209], v146 offset:38912
	ds_read_b128 v[210:213], v147 offset:49152
	ds_read_b128 v[214:217], v147 offset:51200
	ds_read_b128 v[244:247], v147 offset:53248
	ds_read_b128 v[248:251], v147 offset:55296
	s_waitcnt lgkmcnt(8)
	v_mfma_f32_16x16x32_bf16 v[124:127], v[164:167], v[148:151], v[124:127]
	s_waitcnt vmcnt(15)
	v_mfma_f32_16x16x32_bf16 v[120:123], v[168:171], v[148:151], v[120:123]
	ds_write_b128 v143, v[44:47]
	v_mfma_f32_16x16x32_bf16 v[116:119], v[172:175], v[148:151], v[116:119]
	s_waitcnt vmcnt(14)
	v_mfma_f32_16x16x32_bf16 v[112:115], v[178:181], v[148:151], v[112:115]
	ds_write_b128 v143, v[48:51] offset:16384
	v_mfma_f32_16x16x32_bf16 v[108:111], v[164:167], v[152:155], v[108:111]
	s_waitcnt vmcnt(13)
	v_mfma_f32_16x16x32_bf16 v[104:107], v[168:171], v[152:155], v[104:107]
	ds_write_b128 v143, v[56:59] offset:4096
	v_mfma_f32_16x16x32_bf16 v[100:103], v[172:175], v[152:155], v[100:103]
	s_waitcnt vmcnt(12)
	v_mfma_f32_16x16x32_bf16 v[96:99], v[178:181], v[152:155], v[96:99]
	ds_write_b128 v143, v[60:63] offset:20480
	v_mfma_f32_16x16x32_bf16 v[88:91], v[164:167], v[156:159], v[88:91]
	s_waitcnt vmcnt(11)
	v_mfma_f32_16x16x32_bf16 v[84:87], v[168:171], v[156:159], v[84:87]
	ds_write_b128 v143, v[68:71] offset:8192
	v_mfma_f32_16x16x32_bf16 v[72:75], v[172:175], v[156:159], v[72:75]
	s_waitcnt vmcnt(10)
	v_mfma_f32_16x16x32_bf16 v[64:67], v[178:181], v[156:159], v[64:67]
	ds_write_b128 v143, v[76:79] offset:24576
	v_mfma_f32_16x16x32_bf16 v[52:55], v[164:167], v[160:163], v[52:55]
	s_waitcnt vmcnt(9)
	v_mfma_f32_16x16x32_bf16 v[40:43], v[168:171], v[160:163], v[40:43]
	ds_write_b128 v143, v[80:83] offset:12288
	v_mfma_f32_16x16x32_bf16 v[36:39], v[172:175], v[160:163], v[36:39]
	s_waitcnt vmcnt(8)
	v_mfma_f32_16x16x32_bf16 v[24:27], v[178:181], v[160:163], v[24:27]
	ds_write_b128 v143, v[92:95] offset:28672
	s_waitcnt lgkmcnt(0)
	s_barrier
	ds_read_b128 v[148:151], v144
	ds_read_b128 v[152:155], v144 offset:2048
	ds_read_b128 v[156:159], v144 offset:4096
	ds_read_b128 v[160:163], v144 offset:6144
	ds_read_b128 v[164:167], v145 offset:16384
	ds_read_b128 v[168:171], v145 offset:18432
	ds_read_b128 v[172:175], v145 offset:20480
	ds_read_b128 v[178:181], v145 offset:22528
	v_mfma_f32_16x16x32_bf16 v[124:127], v[210:213], v[194:197], v[124:127]
	v_lshl_add_u64 v[80:81], v[138:139], 0, s[56:57]
	v_mfma_f32_16x16x32_bf16 v[120:123], v[214:217], v[194:197], v[120:123]
	v_add_co_u32_e32 v56, vcc, s65, v80
	v_lshl_add_u64 v[92:93], v[140:141], 0, s[56:57]
	v_mfma_f32_16x16x32_bf16 v[116:119], v[244:247], v[194:197], v[116:119]
	s_nop 0
	v_addc_co_u32_e32 v57, vcc, 0, v81, vcc
	v_mfma_f32_16x16x32_bf16 v[112:115], v[248:251], v[194:197], v[112:115]
	v_add_co_u32_e32 v60, vcc, s65, v92
	v_mfma_f32_16x16x32_bf16 v[108:111], v[210:213], v[198:201], v[108:111]
	global_load_dwordx4 v[44:47], v[80:81], off offset:512
	global_load_dwordx4 v[48:51], v[92:93], off offset:512
	v_mfma_f32_16x16x32_bf16 v[104:107], v[214:217], v[198:201], v[104:107]
	v_addc_co_u32_e32 v61, vcc, 0, v93, vcc
	v_add_co_u32_e32 v68, vcc, s46, v80
	v_mfma_f32_16x16x32_bf16 v[100:103], v[244:247], v[198:201], v[100:103]
	global_load_dwordx4 v[56:59], v[56:57], off offset:512
	v_mfma_f32_16x16x32_bf16 v[96:99], v[248:251], v[198:201], v[96:99]
	s_nop 0
	v_addc_co_u32_e32 v69, vcc, 0, v81, vcc
	v_mfma_f32_16x16x32_bf16 v[88:91], v[210:213], v[202:205], v[88:91]
	v_add_co_u32_e32 v76, vcc, s46, v92
	global_load_dwordx4 v[60:63], v[60:61], off offset:512
	v_mfma_f32_16x16x32_bf16 v[84:87], v[214:217], v[202:205], v[84:87]
	s_nop 0
	v_mfma_f32_16x16x32_bf16 v[72:75], v[244:247], v[202:205], v[72:75]
	v_addc_co_u32_e32 v77, vcc, 0, v93, vcc
	v_add_co_u32_e32 v80, vcc, s47, v80
	v_mfma_f32_16x16x32_bf16 v[64:67], v[248:251], v[202:205], v[64:67]
	global_load_dwordx4 v[68:71], v[68:69], off offset:512
	s_nop 0
	v_mfma_f32_16x16x32_bf16 v[52:55], v[210:213], v[206:209], v[52:55]
	v_addc_co_u32_e32 v81, vcc, 0, v81, vcc
	v_mfma_f32_16x16x32_bf16 v[40:43], v[214:217], v[206:209], v[40:43]
	v_add_co_u32_e32 v92, vcc, s47, v92
	global_load_dwordx4 v[76:79], v[76:77], off offset:512
	v_mfma_f32_16x16x32_bf16 v[36:39], v[244:247], v[206:209], v[36:39]
	s_nop 0
	v_addc_co_u32_e32 v93, vcc, 0, v93, vcc
	v_mfma_f32_16x16x32_bf16 v[24:27], v[248:251], v[206:209], v[24:27]
	global_load_dwordx4 v[80:83], v[80:81], off offset:512
	global_load_dwordx4 v[92:95], v[92:93], off offset:512
	s_cbranch_scc1 .Lxk_222
	s_waitcnt vmcnt(0) lgkmcnt(0)
	s_waitcnt vmcnt(15)
	v_mul_f32_e32 v0, 0xbfb8aa3b, v124
	v_mul_f32_e32 v1, 0xbfb8aa3b, v125
	v_exp_f32_e32 v0, v0
	v_exp_f32_e32 v1, v1
	v_mul_f32_e32 v2, 0xbfb8aa3b, v126
	v_mul_f32_e32 v3, 0xbfb8aa3b, v127
	v_exp_f32_e32 v2, v2
	v_exp_f32_e32 v3, v3
	v_add_f32_e32 v0, 1.0, v0
	v_add_f32_e32 v1, 1.0, v1
	v_rcp_f32_e32 v0, v0
	v_rcp_f32_e32 v1, v1
	s_nop 1
	v_cvt_pk_bf16_f32 v173, v0, v1
	v_add_f32_e32 v0, 1.0, v2
	v_add_f32_e32 v1, 1.0, v3
	v_mul_f32_e32 v2, 0xbfb8aa3b, v120
	v_mul_f32_e32 v3, 0xbfb8aa3b, v121
	v_exp_f32_e32 v2, v2
	v_exp_f32_e32 v3, v3
	v_rcp_f32_e32 v0, v0
	v_rcp_f32_e32 v1, v1
	s_nop 1
	v_cvt_pk_bf16_f32 v174, v0, v1
	v_add_f32_e32 v0, 1.0, v2
	v_add_f32_e32 v1, 1.0, v3
	v_mul_f32_e32 v2, 0xbfb8aa3b, v122
	v_mul_f32_e32 v3, 0xbfb8aa3b, v123
	v_exp_f32_e32 v2, v2
	v_exp_f32_e32 v3, v3
	v_rcp_f32_e32 v0, v0
	v_rcp_f32_e32 v1, v1
	s_nop 1
	v_cvt_pk_bf16_f32 v171, v0, v1
	v_add_f32_e32 v0, 1.0, v2
	v_add_f32_e32 v1, 1.0, v3
	v_mul_f32_e32 v2, 0xbfb8aa3b, v116
	v_mul_f32_e32 v3, 0xbfb8aa3b, v117
	v_exp_f32_e32 v2, v2
	v_exp_f32_e32 v3, v3
	v_rcp_f32_e32 v0, v0
	v_rcp_f32_e32 v1, v1
	s_nop 1
	v_cvt_pk_bf16_f32 v172, v0, v1
	v_add_f32_e32 v0, 1.0, v2
	v_add_f32_e32 v1, 1.0, v3
	v_mul_f32_e32 v2, 0xbfb8aa3b, v118
	v_mul_f32_e32 v3, 0xbfb8aa3b, v119
	v_exp_f32_e32 v2, v2
	v_exp_f32_e32 v3, v3
	v_rcp_f32_e32 v0, v0
	v_rcp_f32_e32 v1, v1
	s_nop 1
	v_cvt_pk_bf16_f32 v169, v0, v1
	v_add_f32_e32 v0, 1.0, v2
	v_add_f32_e32 v1, 1.0, v3
	v_mul_f32_e32 v2, 0xbfb8aa3b, v112
	v_mul_f32_e32 v3, 0xbfb8aa3b, v113
	v_exp_f32_e32 v2, v2
	v_exp_f32_e32 v3, v3
	v_rcp_f32_e32 v0, v0
	v_rcp_f32_e32 v1, v1
	s_nop 1
	v_cvt_pk_bf16_f32 v170, v0, v1
	v_add_f32_e32 v0, 1.0, v2
	v_add_f32_e32 v1, 1.0, v3
	v_mul_f32_e32 v2, 0xbfb8aa3b, v114
	v_mul_f32_e32 v3, 0xbfb8aa3b, v115
	v_exp_f32_e32 v2, v2
	v_exp_f32_e32 v3, v3
	v_rcp_f32_e32 v0, v0
	v_rcp_f32_e32 v1, v1
	s_nop 1
	v_cvt_pk_bf16_f32 v167, v0, v1
	v_add_f32_e32 v0, 1.0, v2
	v_add_f32_e32 v1, 1.0, v3
	v_mul_f32_e32 v2, 0xbfb8aa3b, v108
	v_mul_f32_e32 v3, 0xbfb8aa3b, v109
	v_exp_f32_e32 v2, v2
	v_exp_f32_e32 v3, v3
	v_rcp_f32_e32 v0, v0
	v_rcp_f32_e32 v1, v1
	s_nop 1
	v_cvt_pk_bf16_f32 v168, v0, v1
	v_add_f32_e32 v0, 1.0, v2
	v_add_f32_e32 v1, 1.0, v3
	v_mul_f32_e32 v2, 0xbfb8aa3b, v110
	v_mul_f32_e32 v3, 0xbfb8aa3b, v111
	v_exp_f32_e32 v2, v2
	v_exp_f32_e32 v3, v3
	v_rcp_f32_e32 v0, v0
	v_rcp_f32_e32 v1, v1
	s_nop 1
	v_cvt_pk_bf16_f32 v165, v0, v1
	v_add_f32_e32 v0, 1.0, v2
	v_add_f32_e32 v1, 1.0, v3
	v_mul_f32_e32 v2, 0xbfb8aa3b, v104
	v_mul_f32_e32 v3, 0xbfb8aa3b, v105
	v_exp_f32_e32 v2, v2
	v_exp_f32_e32 v3, v3
	v_rcp_f32_e32 v0, v0
	v_rcp_f32_e32 v1, v1
	s_nop 1
	v_cvt_pk_bf16_f32 v166, v0, v1
	v_add_f32_e32 v0, 1.0, v2
	v_add_f32_e32 v1, 1.0, v3
	v_mul_f32_e32 v2, 0xbfb8aa3b, v106
	v_mul_f32_e32 v3, 0xbfb8aa3b, v107
	v_exp_f32_e32 v2, v2
	v_exp_f32_e32 v3, v3
	v_rcp_f32_e32 v0, v0
	v_rcp_f32_e32 v1, v1
	s_nop 1
	v_cvt_pk_bf16_f32 v163, v0, v1
	v_add_f32_e32 v0, 1.0, v2
	v_add_f32_e32 v1, 1.0, v3
	v_mul_f32_e32 v2, 0xbfb8aa3b, v100
	v_mul_f32_e32 v3, 0xbfb8aa3b, v101
	v_exp_f32_e32 v2, v2
	v_exp_f32_e32 v3, v3
	v_rcp_f32_e32 v0, v0
	v_rcp_f32_e32 v1, v1
	s_nop 1
	v_cvt_pk_bf16_f32 v164, v0, v1
	v_add_f32_e32 v0, 1.0, v2
	v_add_f32_e32 v1, 1.0, v3
	v_mul_f32_e32 v2, 0xbfb8aa3b, v102
	v_mul_f32_e32 v3, 0xbfb8aa3b, v103
	v_exp_f32_e32 v2, v2
	v_exp_f32_e32 v3, v3
	v_rcp_f32_e32 v0, v0
	v_rcp_f32_e32 v1, v1
	s_nop 1
	v_cvt_pk_bf16_f32 v161, v0, v1
	v_add_f32_e32 v0, 1.0, v2
	v_add_f32_e32 v1, 1.0, v3
	v_mul_f32_e32 v2, 0xbfb8aa3b, v96
	v_mul_f32_e32 v3, 0xbfb8aa3b, v97
	v_exp_f32_e32 v2, v2
	v_exp_f32_e32 v3, v3
	v_rcp_f32_e32 v0, v0
	v_rcp_f32_e32 v1, v1
	s_nop 1
	v_cvt_pk_bf16_f32 v162, v0, v1
	v_add_f32_e32 v0, 1.0, v2
	v_add_f32_e32 v1, 1.0, v3
	v_mul_f32_e32 v2, 0xbfb8aa3b, v98
	v_mul_f32_e32 v3, 0xbfb8aa3b, v99
	v_exp_f32_e32 v2, v2
	v_exp_f32_e32 v3, v3
	v_rcp_f32_e32 v0, v0
	v_rcp_f32_e32 v1, v1
	s_nop 1
	v_cvt_pk_bf16_f32 v159, v0, v1
	v_add_f32_e32 v0, 1.0, v2
	v_add_f32_e32 v1, 1.0, v3
	v_mul_f32_e32 v2, 0xbfb8aa3b, v88
	v_mul_f32_e32 v3, 0xbfb8aa3b, v89
	v_exp_f32_e32 v2, v2
	v_exp_f32_e32 v3, v3
	v_rcp_f32_e32 v0, v0
	v_rcp_f32_e32 v1, v1
	s_nop 1
	v_cvt_pk_bf16_f32 v160, v0, v1
	v_add_f32_e32 v0, 1.0, v2
	v_add_f32_e32 v1, 1.0, v3
	v_mul_f32_e32 v2, 0xbfb8aa3b, v90
	v_mul_f32_e32 v3, 0xbfb8aa3b, v91
	v_exp_f32_e32 v2, v2
	v_exp_f32_e32 v3, v3
	v_rcp_f32_e32 v0, v0
	v_rcp_f32_e32 v1, v1
	s_nop 1
	v_cvt_pk_bf16_f32 v157, v0, v1
	v_add_f32_e32 v0, 1.0, v2
	v_add_f32_e32 v1, 1.0, v3
	v_mul_f32_e32 v2, 0xbfb8aa3b, v84
	v_mul_f32_e32 v3, 0xbfb8aa3b, v85
	v_exp_f32_e32 v2, v2
	v_exp_f32_e32 v3, v3
	v_rcp_f32_e32 v0, v0
	v_rcp_f32_e32 v1, v1
	s_nop 1
	v_cvt_pk_bf16_f32 v158, v0, v1
	v_add_f32_e32 v0, 1.0, v2
	v_add_f32_e32 v1, 1.0, v3
	v_mul_f32_e32 v2, 0xbfb8aa3b, v86
	v_mul_f32_e32 v3, 0xbfb8aa3b, v87
	v_exp_f32_e32 v2, v2
	v_exp_f32_e32 v3, v3
	v_rcp_f32_e32 v0, v0
	v_rcp_f32_e32 v1, v1
	s_nop 1
	v_cvt_pk_bf16_f32 v155, v0, v1
	v_add_f32_e32 v0, 1.0, v2
	v_add_f32_e32 v1, 1.0, v3
	v_mul_f32_e32 v2, 0xbfb8aa3b, v72
	v_mul_f32_e32 v3, 0xbfb8aa3b, v73
	v_exp_f32_e32 v2, v2
	v_exp_f32_e32 v3, v3
	v_rcp_f32_e32 v0, v0
	v_rcp_f32_e32 v1, v1
	s_nop 1
	v_cvt_pk_bf16_f32 v156, v0, v1
	v_add_f32_e32 v0, 1.0, v2
	v_add_f32_e32 v1, 1.0, v3
	v_mul_f32_e32 v2, 0xbfb8aa3b, v74
	v_mul_f32_e32 v3, 0xbfb8aa3b, v75
	v_exp_f32_e32 v2, v2
	v_exp_f32_e32 v3, v3
	v_rcp_f32_e32 v0, v0
	v_rcp_f32_e32 v1, v1
	s_nop 1
	v_cvt_pk_bf16_f32 v153, v0, v1
	v_add_f32_e32 v0, 1.0, v2
	v_add_f32_e32 v1, 1.0, v3
	v_mul_f32_e32 v2, 0xbfb8aa3b, v64
	v_mul_f32_e32 v3, 0xbfb8aa3b, v65
	v_exp_f32_e32 v2, v2
	v_exp_f32_e32 v3, v3
	v_rcp_f32_e32 v0, v0
	v_rcp_f32_e32 v1, v1
	s_nop 1
	v_cvt_pk_bf16_f32 v154, v0, v1
	v_add_f32_e32 v0, 1.0, v2
	v_add_f32_e32 v1, 1.0, v3
	v_mul_f32_e32 v2, 0xbfb8aa3b, v66
	v_mul_f32_e32 v3, 0xbfb8aa3b, v67
	v_exp_f32_e32 v2, v2
	v_exp_f32_e32 v3, v3
	v_rcp_f32_e32 v0, v0
	v_rcp_f32_e32 v1, v1
	s_nop 1
	v_cvt_pk_bf16_f32 v151, v0, v1
	v_add_f32_e32 v0, 1.0, v2
	v_add_f32_e32 v1, 1.0, v3
	v_mul_f32_e32 v2, 0xbfb8aa3b, v52
	v_mul_f32_e32 v3, 0xbfb8aa3b, v53
	v_exp_f32_e32 v2, v2
	v_exp_f32_e32 v3, v3
	v_rcp_f32_e32 v0, v0
	v_rcp_f32_e32 v1, v1
	s_nop 1
	v_cvt_pk_bf16_f32 v152, v0, v1
	v_add_f32_e32 v0, 1.0, v2
	v_add_f32_e32 v1, 1.0, v3
	v_mul_f32_e32 v2, 0xbfb8aa3b, v54
	v_mul_f32_e32 v3, 0xbfb8aa3b, v55
	v_exp_f32_e32 v2, v2
	v_exp_f32_e32 v3, v3
	v_rcp_f32_e32 v0, v0
	v_rcp_f32_e32 v1, v1
	s_nop 1
	v_cvt_pk_bf16_f32 v149, v0, v1
	v_add_f32_e32 v0, 1.0, v2
	v_add_f32_e32 v1, 1.0, v3
	v_mul_f32_e32 v2, 0xbfb8aa3b, v40
	v_mul_f32_e32 v3, 0xbfb8aa3b, v41
	v_exp_f32_e32 v2, v2
	v_exp_f32_e32 v3, v3
	v_rcp_f32_e32 v0, v0
	v_rcp_f32_e32 v1, v1
	s_nop 1
	v_cvt_pk_bf16_f32 v150, v0, v1
	v_add_f32_e32 v0, 1.0, v2
	v_add_f32_e32 v1, 1.0, v3
	v_mul_f32_e32 v2, 0xbfb8aa3b, v42
	v_mul_f32_e32 v3, 0xbfb8aa3b, v43
	v_exp_f32_e32 v2, v2
	v_exp_f32_e32 v3, v3
	v_rcp_f32_e32 v0, v0
	v_rcp_f32_e32 v1, v1
	s_nop 1
	v_cvt_pk_bf16_f32 v146, v0, v1
	v_add_f32_e32 v0, 1.0, v2
	v_add_f32_e32 v1, 1.0, v3
	v_mul_f32_e32 v2, 0xbfb8aa3b, v36
	v_mul_f32_e32 v3, 0xbfb8aa3b, v37
	v_exp_f32_e32 v2, v2
	v_exp_f32_e32 v3, v3
	v_rcp_f32_e32 v0, v0
	v_rcp_f32_e32 v1, v1
	s_nop 1
	v_cvt_pk_bf16_f32 v148, v0, v1
	v_add_f32_e32 v0, 1.0, v2
	v_add_f32_e32 v1, 1.0, v3
	v_mul_f32_e32 v2, 0xbfb8aa3b, v38
	v_mul_f32_e32 v3, 0xbfb8aa3b, v39
	s_waitcnt vmcnt(14)
	v_mul_f32_e32 v4, 0xbfb8aa3b, v24
	v_mul_f32_e32 v5, 0xbfb8aa3b, v25
	v_mul_f32_e32 v6, 0xbfb8aa3b, v26
	v_mul_f32_e32 v7, 0xbfb8aa3b, v27
	v_exp_f32_e32 v2, v2
	v_exp_f32_e32 v3, v3
	v_exp_f32_e32 v4, v4
	v_exp_f32_e32 v5, v5
	v_exp_f32_e32 v6, v6
	v_exp_f32_e32 v7, v7
	v_add_f32_e32 v2, 1.0, v2
	v_add_f32_e32 v3, 1.0, v3
	v_add_f32_e32 v4, 1.0, v4
	v_add_f32_e32 v5, 1.0, v5
	v_add_f32_e32 v6, 1.0, v6
	v_add_f32_e32 v7, 1.0, v7
	v_rcp_f32_e32 v0, v0
	v_rcp_f32_e32 v1, v1
	v_rcp_f32_e32 v2, v2
	v_rcp_f32_e32 v3, v3
	v_rcp_f32_e32 v4, v4
	v_rcp_f32_e32 v5, v5
	v_rcp_f32_e32 v6, v6
	v_rcp_f32_e32 v7, v7
	s_mov_b64 s[18:19], -1
	s_and_b64 vcc, exec, s[16:17]
	s_nop 1
	v_cvt_pk_bf16_f32 v147, v0, v1
	s_nop 1
	v_cvt_pk_bf16_f32 v145, v2, v3
	s_nop 1
	v_cvt_pk_bf16_f32 v144, v4, v5
	s_nop 1
	v_cvt_pk_bf16_f32 v143, v6, v7
	s_cbranch_vccz .LBB0_227
	s_waitcnt vmcnt(7)
	v_mov_b32_e32 v46, v192
	s_movk_i32 s7, 0x70
	v_ashrrev_i32_e32 v32, 3, v46
	v_ashrrev_i32_e32 v33, 31, v32
	v_lshlrev_b64 v[0:1], 12, v[32:33]
	v_lshlrev_b32_e32 v4, 4, v46
	v_lshl_add_u64 v[2:3], s[8:9], 0, v[0:1]
	v_and_b32_e32 v176, 0x70, v4
	v_lshl_add_u64 v[138:139], v[2:3], 0, v[176:177]
	v_lshl_add_u64 v[0:1], s[10:11], 0, v[0:1]
	v_add_co_u32_e32 v34, vcc, 0x20000, v138
	v_lshl_add_u64 v[140:141], v[0:1], 0, v[176:177]
	s_nop 0
	v_addc_co_u32_e32 v35, vcc, 0, v139, vcc
	v_add_co_u32_e32 v36, vcc, 0x20000, v140
	global_load_dwordx4 v[0:3], v[138:139], off
	global_load_dwordx4 v[4:7], v[140:141], off
	v_addc_co_u32_e32 v37, vcc, 0, v141, vcc
	v_add_co_u32_e32 v38, vcc, s33, v138
	global_load_dwordx4 v[8:11], v[34:35], off
	global_load_dwordx4 v[12:15], v[36:37], off
	v_addc_co_u32_e32 v39, vcc, 0, v139, vcc
	v_add_co_u32_e32 v40, vcc, s33, v140
	global_load_dwordx4 v[16:19], v[38:39], off
	s_nop 0
	v_addc_co_u32_e32 v41, vcc, 0, v141, vcc
	v_add_co_u32_e32 v42, vcc, 0x60000, v138
	global_load_dwordx4 v[20:23], v[40:41], off
	s_nop 0
	v_addc_co_u32_e32 v43, vcc, 0, v139, vcc
	v_add_co_u32_e32 v44, vcc, 0x60000, v140
	global_load_dwordx4 v[24:27], v[42:43], off
	s_nop 0
	v_addc_co_u32_e32 v45, vcc, 0, v141, vcc
	global_load_dwordx4 v[28:31], v[44:45], off
	global_load_dwordx4 v[64:67], v[138:139], off offset:128
	global_load_dwordx4 v[68:71], v[140:141], off offset:128
	global_load_dwordx4 v[72:75], v[34:35], off offset:128
	global_load_dwordx4 v[76:79], v[36:37], off offset:128
	global_load_dwordx4 v[80:83], v[38:39], off offset:128
	global_load_dwordx4 v[84:87], v[40:41], off offset:128
	global_load_dwordx4 v[88:91], v[42:43], off offset:128
	global_load_dwordx4 v[92:95], v[44:45], off offset:128
	s_barrier
	global_load_dwordx4 v[96:99], v[138:139], off offset:256
	global_load_dwordx4 v[100:103], v[140:141], off offset:256
	global_load_dwordx4 v[104:107], v[34:35], off offset:256
	global_load_dwordx4 v[108:111], v[36:37], off offset:256
	global_load_dwordx4 v[112:115], v[38:39], off offset:256
	global_load_dwordx4 v[116:119], v[40:41], off offset:256
	global_load_dwordx4 v[120:123], v[42:43], off offset:256
	global_load_dwordx4 v[124:127], v[44:45], off offset:256
	s_waitcnt vmcnt(30)
	v_lshlrev_b32_e32 v51, 7, v32
	v_lshrrev_b32_e32 v32, 1, v32
	v_xor_b32_e32 v32, v32, v46
	v_lshlrev_b32_e32 v32, 4, v32
	v_lshrrev_b32_e32 v33, 4, v46
	v_bfe_u32 v47, v46, 4, 2
	v_bfe_u32 v48, v46, 1, 3
	v_and_or_b32 v175, v32, s7, v51
	v_lshlrev_b32_e32 v49, 6, v46
	v_lshlrev_b32_e32 v50, 7, v46
	v_bitop3_b32 v33, v33, v48, 3 bitop3:0x6c
	v_and_b32_e32 v49, 0xffffe000, v49
	v_and_b32_e32 v52, 0x780, v50
	v_and_b32_e32 v50, 0x2000, v50
	v_lshlrev_b32_e32 v33, 4, v33
	v_or_b32_e32 v46, v33, v49
	s_mov_b32 s7, -2
	v_add_u32_e32 v176, v46, v52
	s_waitcnt vmcnt(23)
	ds_write_b128 v175, v[0:3]
	s_waitcnt vmcnt(22)
	ds_write_b128 v175, v[4:7] offset:16384
	s_waitcnt vmcnt(21)
	ds_write_b128 v175, v[8:11] offset:4096
	s_waitcnt vmcnt(20)
	ds_write_b128 v175, v[12:15] offset:20480
	s_waitcnt vmcnt(19)
	ds_write_b128 v175, v[16:19] offset:8192
	s_waitcnt vmcnt(18)
	ds_write_b128 v175, v[20:23] offset:24576
	s_waitcnt vmcnt(17)
	ds_write_b128 v175, v[24:27] offset:12288
	s_waitcnt vmcnt(16)
	ds_write_b128 v175, v[28:31] offset:28672
	v_bitop3_b32 v0, v47, v48, 4 bitop3:0x36
	v_lshlrev_b32_e32 v0, 4, v0
	v_or_b32_e32 v1, v33, v50
	v_or_b32_e32 v2, v0, v49
	v_or_b32_e32 v3, v0, v50
	v_mov_b32_e32 v0, 0
	v_add_u32_e32 v178, v1, v52
	v_add_u32_e32 v179, v2, v52
	v_add_u32_e32 v180, v3, v52
	v_mov_b32_e32 v1, v0
	v_mov_b32_e32 v2, v0
	v_mov_b32_e32 v3, v0
	v_mov_b32_e32 v4, v0
	v_mov_b32_e32 v5, v0
	v_mov_b32_e32 v6, v0
	v_mov_b32_e32 v7, v0
	v_mov_b32_e32 v8, v0
	v_mov_b32_e32 v9, v0
	v_mov_b32_e32 v10, v0
	v_mov_b32_e32 v11, v0
	v_mov_b32_e32 v12, v0
	v_mov_b32_e32 v13, v0
	v_mov_b32_e32 v14, v0
	v_mov_b32_e32 v15, v0
	v_mov_b32_e32 v16, v0
	v_mov_b32_e32 v17, v0
	v_mov_b32_e32 v18, v0
	v_mov_b32_e32 v19, v0
	v_mov_b32_e32 v20, v0
	v_mov_b32_e32 v21, v0
	v_mov_b32_e32 v22, v0
	v_mov_b32_e32 v23, v0
	v_mov_b32_e32 v24, v0
	v_mov_b32_e32 v25, v0
	v_mov_b32_e32 v26, v0
	v_mov_b32_e32 v27, v0
	v_mov_b32_e32 v28, v0
	v_mov_b32_e32 v29, v0
	v_mov_b32_e32 v30, v0
	v_mov_b32_e32 v31, v0
	v_mov_b32_e32 v32, v0
	v_mov_b32_e32 v33, v0
	v_mov_b32_e32 v34, v0
	v_mov_b32_e32 v35, v0
	v_mov_b32_e32 v36, v0
	v_mov_b32_e32 v37, v0
	v_mov_b32_e32 v38, v0
	v_mov_b32_e32 v39, v0
	v_mov_b32_e32 v40, v0
	v_mov_b32_e32 v41, v0
	v_mov_b32_e32 v42, v0
	v_mov_b32_e32 v43, v0
	v_mov_b32_e32 v44, v0
	v_mov_b32_e32 v45, v0
	v_mov_b32_e32 v46, v0
	v_mov_b32_e32 v47, v0
	v_mov_b32_e32 v48, v0
	v_mov_b32_e32 v49, v0
	v_mov_b32_e32 v50, v0
	v_mov_b32_e32 v51, v0
	v_mov_b32_e32 v52, v0
	v_mov_b32_e32 v53, v0
	v_mov_b32_e32 v54, v0
	v_mov_b32_e32 v55, v0
	v_mov_b32_e32 v56, v0
	v_mov_b32_e32 v57, v0
	v_mov_b32_e32 v58, v0
	v_mov_b32_e32 v59, v0
	v_mov_b32_e32 v60, v0
	v_mov_b32_e32 v61, v0
	v_mov_b32_e32 v62, v0
	v_mov_b32_e32 v63, v0
	s_waitcnt lgkmcnt(0)
	s_barrier

.Lxk_225:
	ds_read_b128 v[194:197], v179
	ds_read_b128 v[198:201], v179 offset:2048
	ds_read_b128 v[202:205], v179 offset:4096
	ds_read_b128 v[206:209], v179 offset:6144
	ds_read_b128 v[210:213], v180 offset:16384
	ds_read_b128 v[214:217], v180 offset:18432
	ds_read_b128 v[244:247], v180 offset:20480
	ds_read_b128 v[248:251], v180 offset:22528
	s_waitcnt lgkmcnt(8)
	v_mfma_f32_16x16x32_bf16 v[60:63], v[228:231], v[182:185], v[60:63]
	s_add_i32 s7, s7, 2
	v_mfma_f32_16x16x32_bf16 v[56:59], v[232:235], v[182:185], v[56:59]
	s_min_u32 s18, s7, 28
	v_mfma_f32_16x16x32_bf16 v[52:55], v[236:239], v[182:185], v[52:55]
	s_lshl_b32 s56, s18, 7
	v_mfma_f32_16x16x32_bf16 v[48:51], v[240:243], v[182:185], v[48:51]
	s_min_u32 s18, s7, 27
	s_waitcnt vmcnt(15)
	v_mfma_f32_16x16x32_bf16 v[44:47], v[228:231], v[186:189], v[44:47]
	ds_write_b128 v175, v[64:67] offset:32768
	v_mfma_f32_16x16x32_bf16 v[40:43], v[232:235], v[186:189], v[40:43]
	s_waitcnt vmcnt(14)
	v_mfma_f32_16x16x32_bf16 v[36:39], v[236:239], v[186:189], v[36:39]
	ds_write_b128 v175, v[68:71] offset:49152
	v_mfma_f32_16x16x32_bf16 v[32:35], v[240:243], v[186:189], v[32:35]
	s_waitcnt vmcnt(13)
	ds_write_b128 v175, v[72:75] offset:36864
	v_mfma_f32_16x16x32_bf16 v[28:31], v[228:231], v[220:223], v[28:31]
	s_waitcnt vmcnt(12)
	v_mfma_f32_16x16x32_bf16 v[24:27], v[232:235], v[220:223], v[24:27]
	ds_write_b128 v175, v[76:79] offset:53248
	v_mfma_f32_16x16x32_bf16 v[20:23], v[236:239], v[220:223], v[20:23]
	s_waitcnt vmcnt(11)
	v_mfma_f32_16x16x32_bf16 v[16:19], v[240:243], v[220:223], v[16:19]
	ds_write_b128 v175, v[80:83] offset:40960
	s_waitcnt vmcnt(10)
	v_mfma_f32_16x16x32_bf16 v[12:15], v[228:231], v[224:227], v[12:15]
	ds_write_b128 v175, v[84:87] offset:57344
	v_mfma_f32_16x16x32_bf16 v[8:11], v[232:235], v[224:227], v[8:11]
	s_waitcnt vmcnt(9)
	v_mfma_f32_16x16x32_bf16 v[4:7], v[236:239], v[224:227], v[4:7]
	ds_write_b128 v175, v[88:91] offset:45056
	v_mfma_f32_16x16x32_bf16 v[0:3], v[240:243], v[224:227], v[0:3]
	s_waitcnt vmcnt(8)
	ds_write_b128 v175, v[92:95] offset:61440
	s_waitcnt lgkmcnt(0)
	s_barrier
	ds_read_b128 v[182:185], v176 offset:32768
	ds_read_b128 v[186:189], v176 offset:34816
	ds_read_b128 v[220:223], v176 offset:36864
	ds_read_b128 v[224:227], v176 offset:38912
	ds_read_b128 v[228:231], v178 offset:49152
	ds_read_b128 v[232:235], v178 offset:51200
	ds_read_b128 v[236:239], v178 offset:53248
	ds_read_b128 v[240:243], v178 offset:55296
	v_mfma_f32_16x16x32_bf16 v[60:63], v[210:213], v[194:197], v[60:63]
	v_lshl_add_u64 v[88:89], v[138:139], 0, s[56:57]
	v_mfma_f32_16x16x32_bf16 v[56:59], v[214:217], v[194:197], v[56:59]
	v_add_co_u32_e32 v72, vcc, s46, v88
	v_lshl_add_u64 v[92:93], v[140:141], 0, s[56:57]
	v_mfma_f32_16x16x32_bf16 v[52:55], v[244:247], v[194:197], v[52:55]
	s_nop 0
	v_mfma_f32_16x16x32_bf16 v[48:51], v[248:251], v[194:197], v[48:51]
	v_addc_co_u32_e32 v73, vcc, 0, v89, vcc
	v_add_co_u32_e32 v76, vcc, s46, v92
	v_mfma_f32_16x16x32_bf16 v[44:47], v[210:213], v[198:201], v[44:47]
	global_load_dwordx4 v[64:67], v[88:89], off offset:384
	v_mfma_f32_16x16x32_bf16 v[40:43], v[214:217], v[198:201], v[40:43]
	global_load_dwordx4 v[68:71], v[92:93], off offset:384
	v_addc_co_u32_e32 v77, vcc, 0, v93, vcc
	v_mfma_f32_16x16x32_bf16 v[36:39], v[244:247], v[198:201], v[36:39]
	v_add_co_u32_e32 v80, vcc, s33, v88
	v_mfma_f32_16x16x32_bf16 v[32:35], v[248:251], v[198:201], v[32:35]
	s_nop 0
	v_addc_co_u32_e32 v81, vcc, 0, v89, vcc
	v_add_co_u32_e32 v84, vcc, s33, v92
	v_mfma_f32_16x16x32_bf16 v[28:31], v[210:213], v[202:205], v[28:31]
	s_nop 0
	v_addc_co_u32_e32 v85, vcc, 0, v93, vcc
	v_add_co_u32_e32 v88, vcc, s48, v88
	v_mfma_f32_16x16x32_bf16 v[24:27], v[214:217], v[202:205], v[24:27]
	s_nop 0
	v_addc_co_u32_e32 v89, vcc, 0, v89, vcc
	v_mfma_f32_16x16x32_bf16 v[20:23], v[244:247], v[202:205], v[20:23]
	v_add_co_u32_e32 v92, vcc, s48, v92
	s_nop 1
	v_addc_co_u32_e32 v93, vcc, 0, v93, vcc
	v_mfma_f32_16x16x32_bf16 v[16:19], v[248:251], v[202:205], v[16:19]
	global_load_dwordx4 v[72:75], v[72:73], off offset:384
	v_mfma_f32_16x16x32_bf16 v[12:15], v[210:213], v[206:209], v[12:15]
	global_load_dwordx4 v[76:79], v[76:77], off offset:384
	s_lshl_b32 s56, s18, 7
	v_mfma_f32_16x16x32_bf16 v[8:11], v[214:217], v[206:209], v[8:11]
	global_load_dwordx4 v[80:83], v[80:81], off offset:384
	v_mfma_f32_16x16x32_bf16 v[4:7], v[244:247], v[206:209], v[4:7]
	global_load_dwordx4 v[84:87], v[84:85], off offset:384
	s_cmp_lt_u32 s7, 30
	v_mfma_f32_16x16x32_bf16 v[0:3], v[248:251], v[206:209], v[0:3]
	global_load_dwordx4 v[88:91], v[88:89], off offset:384
	global_load_dwordx4 v[92:95], v[92:93], off offset:384
	ds_read_b128 v[194:197], v179 offset:32768
	ds_read_b128 v[198:201], v179 offset:34816
	ds_read_b128 v[202:205], v179 offset:36864
	ds_read_b128 v[206:209], v179 offset:38912
	ds_read_b128 v[210:213], v180 offset:49152
	ds_read_b128 v[214:217], v180 offset:51200
	ds_read_b128 v[244:247], v180 offset:53248
	ds_read_b128 v[248:251], v180 offset:55296
	s_waitcnt lgkmcnt(8)
	v_mfma_f32_16x16x32_bf16 v[60:63], v[228:231], v[182:185], v[60:63]
	s_waitcnt vmcnt(15)
	v_mfma_f32_16x16x32_bf16 v[56:59], v[232:235], v[182:185], v[56:59]
	ds_write_b128 v175, v[96:99]
	v_mfma_f32_16x16x32_bf16 v[52:55], v[236:239], v[182:185], v[52:55]
	s_waitcnt vmcnt(14)
	v_mfma_f32_16x16x32_bf16 v[48:51], v[240:243], v[182:185], v[48:51]
	ds_write_b128 v175, v[100:103] offset:16384
	v_mfma_f32_16x16x32_bf16 v[44:47], v[228:231], v[186:189], v[44:47]
	s_waitcnt vmcnt(13)
	v_mfma_f32_16x16x32_bf16 v[40:43], v[232:235], v[186:189], v[40:43]
	ds_write_b128 v175, v[104:107] offset:4096
	v_mfma_f32_16x16x32_bf16 v[36:39], v[236:239], v[186:189], v[36:39]
	s_waitcnt vmcnt(12)
	v_mfma_f32_16x16x32_bf16 v[32:35], v[240:243], v[186:189], v[32:35]
	ds_write_b128 v175, v[108:111] offset:20480
	v_mfma_f32_16x16x32_bf16 v[28:31], v[228:231], v[220:223], v[28:31]
	s_waitcnt vmcnt(11)
	v_mfma_f32_16x16x32_bf16 v[24:27], v[232:235], v[220:223], v[24:27]
	ds_write_b128 v175, v[112:115] offset:8192
	v_mfma_f32_16x16x32_bf16 v[20:23], v[236:239], v[220:223], v[20:23]
	s_waitcnt vmcnt(10)
	v_mfma_f32_16x16x32_bf16 v[16:19], v[240:243], v[220:223], v[16:19]
	ds_write_b128 v175, v[116:119] offset:24576
	v_mfma_f32_16x16x32_bf16 v[12:15], v[228:231], v[224:227], v[12:15]
	s_waitcnt vmcnt(9)
	v_mfma_f32_16x16x32_bf16 v[8:11], v[232:235], v[224:227], v[8:11]
	ds_write_b128 v175, v[120:123] offset:12288
	v_mfma_f32_16x16x32_bf16 v[4:7], v[236:239], v[224:227], v[4:7]
	s_waitcnt vmcnt(8)
	v_mfma_f32_16x16x32_bf16 v[0:3], v[240:243], v[224:227], v[0:3]
	ds_write_b128 v175, v[124:127] offset:28672
	s_waitcnt lgkmcnt(0)
	s_barrier
	ds_read_b128 v[182:185], v176
	ds_read_b128 v[186:189], v176 offset:2048
	ds_read_b128 v[220:223], v176 offset:4096
	ds_read_b128 v[224:227], v176 offset:6144
	ds_read_b128 v[228:231], v178 offset:16384
	ds_read_b128 v[232:235], v178 offset:18432
	ds_read_b128 v[236:239], v178 offset:20480
	ds_read_b128 v[240:243], v178 offset:22528
	v_mfma_f32_16x16x32_bf16 v[60:63], v[210:213], v[194:197], v[60:63]
	v_lshl_add_u64 v[120:121], v[138:139], 0, s[56:57]
	v_mfma_f32_16x16x32_bf16 v[56:59], v[214:217], v[194:197], v[56:59]
	v_add_co_u32_e32 v104, vcc, s46, v120
	v_lshl_add_u64 v[124:125], v[140:141], 0, s[56:57]
	v_mfma_f32_16x16x32_bf16 v[52:55], v[244:247], v[194:197], v[52:55]
	s_nop 0
	v_addc_co_u32_e32 v105, vcc, 0, v121, vcc
	v_mfma_f32_16x16x32_bf16 v[48:51], v[248:251], v[194:197], v[48:51]
	v_add_co_u32_e32 v108, vcc, s46, v124
	v_mfma_f32_16x16x32_bf16 v[44:47], v[210:213], v[198:201], v[44:47]
	global_load_dwordx4 v[96:99], v[120:121], off offset:512
	global_load_dwordx4 v[100:103], v[124:125], off offset:512
	v_mfma_f32_16x16x32_bf16 v[40:43], v[214:217], v[198:201], v[40:43]
	v_addc_co_u32_e32 v109, vcc, 0, v125, vcc
	v_add_co_u32_e32 v112, vcc, s33, v120
	v_mfma_f32_16x16x32_bf16 v[36:39], v[244:247], v[198:201], v[36:39]
	global_load_dwordx4 v[104:107], v[104:105], off offset:512
	v_mfma_f32_16x16x32_bf16 v[32:35], v[248:251], v[198:201], v[32:35]
	s_nop 0
	v_addc_co_u32_e32 v113, vcc, 0, v121, vcc
	v_mfma_f32_16x16x32_bf16 v[28:31], v[210:213], v[202:205], v[28:31]
	v_add_co_u32_e32 v116, vcc, s33, v124
	global_load_dwordx4 v[108:111], v[108:109], off offset:512
	v_mfma_f32_16x16x32_bf16 v[24:27], v[214:217], v[202:205], v[24:27]
	s_nop 0
	v_mfma_f32_16x16x32_bf16 v[20:23], v[244:247], v[202:205], v[20:23]
	v_addc_co_u32_e32 v117, vcc, 0, v125, vcc
	v_add_co_u32_e32 v120, vcc, s48, v120
	v_mfma_f32_16x16x32_bf16 v[16:19], v[248:251], v[202:205], v[16:19]
	global_load_dwordx4 v[112:115], v[112:113], off offset:512
	s_nop 0
	v_mfma_f32_16x16x32_bf16 v[12:15], v[210:213], v[206:209], v[12:15]
	v_addc_co_u32_e32 v121, vcc, 0, v121, vcc
	v_mfma_f32_16x16x32_bf16 v[8:11], v[214:217], v[206:209], v[8:11]
	v_add_co_u32_e32 v124, vcc, s48, v124
	global_load_dwordx4 v[116:119], v[116:117], off offset:512
	v_mfma_f32_16x16x32_bf16 v[4:7], v[244:247], v[206:209], v[4:7]
	s_nop 0
	v_addc_co_u32_e32 v125, vcc, 0, v125, vcc
	v_mfma_f32_16x16x32_bf16 v[0:3], v[248:251], v[206:209], v[0:3]
	global_load_dwordx4 v[120:123], v[120:121], off offset:512
	global_load_dwordx4 v[124:127], v[124:125], off offset:512
	s_cbranch_scc1 .Lxk_225
	s_waitcnt vmcnt(0) lgkmcnt(0)
	s_mov_b64 s[18:19], 0

.Lxk_229:
	ds_read_b128 v[194:197], v179
	ds_read_b128 v[198:201], v179 offset:2048
	ds_read_b128 v[202:205], v179 offset:4096
	ds_read_b128 v[206:209], v179 offset:6144
	ds_read_b128 v[210:213], v180 offset:16384
	ds_read_b128 v[214:217], v180 offset:18432
	ds_read_b128 v[244:247], v180 offset:20480
	ds_read_b128 v[248:251], v180 offset:22528
	s_waitcnt lgkmcnt(8)
	v_mfma_f32_16x16x32_bf16 v[60:63], v[228:231], v[182:185], v[60:63]
	s_add_i32 s7, s7, 2
	v_mfma_f32_16x16x32_bf16 v[56:59], v[232:235], v[182:185], v[56:59]
	s_min_u32 s18, s7, 16
	v_mfma_f32_16x16x32_bf16 v[52:55], v[236:239], v[182:185], v[52:55]
	s_lshl_b32 s56, s18, 7
	v_mfma_f32_16x16x32_bf16 v[48:51], v[240:243], v[182:185], v[48:51]
	s_min_u32 s18, s7, 15
	s_waitcnt vmcnt(15)
	v_mfma_f32_16x16x32_bf16 v[44:47], v[228:231], v[186:189], v[44:47]
	ds_write_b128 v175, v[64:67] offset:32768
	v_mfma_f32_16x16x32_bf16 v[40:43], v[232:235], v[186:189], v[40:43]
	s_waitcnt vmcnt(14)
	v_mfma_f32_16x16x32_bf16 v[36:39], v[236:239], v[186:189], v[36:39]
	ds_write_b128 v175, v[68:71] offset:49152
	v_mfma_f32_16x16x32_bf16 v[32:35], v[240:243], v[186:189], v[32:35]
	s_waitcnt vmcnt(13)
	ds_write_b128 v175, v[72:75] offset:36864
	v_mfma_f32_16x16x32_bf16 v[28:31], v[228:231], v[220:223], v[28:31]
	s_waitcnt vmcnt(12)
	v_mfma_f32_16x16x32_bf16 v[24:27], v[232:235], v[220:223], v[24:27]
	ds_write_b128 v175, v[76:79] offset:53248
	v_mfma_f32_16x16x32_bf16 v[20:23], v[236:239], v[220:223], v[20:23]
	s_waitcnt vmcnt(11)
	v_mfma_f32_16x16x32_bf16 v[16:19], v[240:243], v[220:223], v[16:19]
	ds_write_b128 v175, v[80:83] offset:40960
	s_waitcnt vmcnt(10)
	v_mfma_f32_16x16x32_bf16 v[12:15], v[228:231], v[224:227], v[12:15]
	ds_write_b128 v175, v[84:87] offset:57344
	v_mfma_f32_16x16x32_bf16 v[8:11], v[232:235], v[224:227], v[8:11]
	s_waitcnt vmcnt(9)
	v_mfma_f32_16x16x32_bf16 v[4:7], v[236:239], v[224:227], v[4:7]
	ds_write_b128 v175, v[88:91] offset:45056
	v_mfma_f32_16x16x32_bf16 v[0:3], v[240:243], v[224:227], v[0:3]
	s_waitcnt vmcnt(8)
	ds_write_b128 v175, v[92:95] offset:61440
	s_waitcnt lgkmcnt(0)
	s_barrier
	ds_read_b128 v[182:185], v176 offset:32768
	ds_read_b128 v[186:189], v176 offset:34816
	ds_read_b128 v[220:223], v176 offset:36864
	ds_read_b128 v[224:227], v176 offset:38912
	ds_read_b128 v[228:231], v178 offset:49152
	ds_read_b128 v[232:235], v178 offset:51200
	ds_read_b128 v[236:239], v178 offset:53248
	ds_read_b128 v[240:243], v178 offset:55296
	v_mfma_f32_16x16x32_bf16 v[60:63], v[210:213], v[194:197], v[60:63]
	v_lshl_add_u64 v[88:89], v[138:139], 0, s[56:57]
	v_mfma_f32_16x16x32_bf16 v[56:59], v[214:217], v[194:197], v[56:59]
	v_add_co_u32_e32 v72, vcc, s49, v88
	v_lshl_add_u64 v[92:93], v[140:141], 0, s[56:57]
	v_mfma_f32_16x16x32_bf16 v[52:55], v[244:247], v[194:197], v[52:55]
	s_nop 0
	v_mfma_f32_16x16x32_bf16 v[48:51], v[248:251], v[194:197], v[48:51]
	v_addc_co_u32_e32 v73, vcc, 0, v89, vcc
	v_add_co_u32_e32 v76, vcc, s49, v92
	v_mfma_f32_16x16x32_bf16 v[44:47], v[210:213], v[198:201], v[44:47]
	global_load_dwordx4 v[64:67], v[88:89], off offset:384
	v_mfma_f32_16x16x32_bf16 v[40:43], v[214:217], v[198:201], v[40:43]
	global_load_dwordx4 v[68:71], v[92:93], off offset:384
	v_addc_co_u32_e32 v77, vcc, 0, v93, vcc
	v_mfma_f32_16x16x32_bf16 v[36:39], v[244:247], v[198:201], v[36:39]
	v_add_co_u32_e32 v80, vcc, s50, v88
	v_mfma_f32_16x16x32_bf16 v[32:35], v[248:251], v[198:201], v[32:35]
	s_nop 0
	v_addc_co_u32_e32 v81, vcc, 0, v89, vcc
	v_add_co_u32_e32 v84, vcc, s50, v92
	v_mfma_f32_16x16x32_bf16 v[28:31], v[210:213], v[202:205], v[28:31]
	s_nop 0
	v_addc_co_u32_e32 v85, vcc, 0, v93, vcc
	v_add_co_u32_e32 v88, vcc, s51, v88
	v_mfma_f32_16x16x32_bf16 v[24:27], v[214:217], v[202:205], v[24:27]
	s_nop 0
	v_addc_co_u32_e32 v89, vcc, 0, v89, vcc
	v_mfma_f32_16x16x32_bf16 v[20:23], v[244:247], v[202:205], v[20:23]
	v_add_co_u32_e32 v92, vcc, s51, v92
	s_nop 1
	v_addc_co_u32_e32 v93, vcc, 0, v93, vcc
	v_mfma_f32_16x16x32_bf16 v[16:19], v[248:251], v[202:205], v[16:19]
	global_load_dwordx4 v[72:75], v[72:73], off offset:384
	v_mfma_f32_16x16x32_bf16 v[12:15], v[210:213], v[206:209], v[12:15]
	global_load_dwordx4 v[76:79], v[76:77], off offset:384
	s_lshl_b32 s56, s18, 7
	v_mfma_f32_16x16x32_bf16 v[8:11], v[214:217], v[206:209], v[8:11]
	global_load_dwordx4 v[80:83], v[80:81], off offset:384
	v_mfma_f32_16x16x32_bf16 v[4:7], v[244:247], v[206:209], v[4:7]
	global_load_dwordx4 v[84:87], v[84:85], off offset:384
	s_cmp_gt_u32 s7, 17
	v_mfma_f32_16x16x32_bf16 v[0:3], v[248:251], v[206:209], v[0:3]
	global_load_dwordx4 v[88:91], v[88:89], off offset:384
	global_load_dwordx4 v[92:95], v[92:93], off offset:384
	ds_read_b128 v[194:197], v179 offset:32768
	ds_read_b128 v[198:201], v179 offset:34816
	ds_read_b128 v[202:205], v179 offset:36864
	ds_read_b128 v[206:209], v179 offset:38912
	ds_read_b128 v[210:213], v180 offset:49152
	ds_read_b128 v[214:217], v180 offset:51200
	ds_read_b128 v[244:247], v180 offset:53248
	ds_read_b128 v[248:251], v180 offset:55296
	s_waitcnt lgkmcnt(8)
	v_mfma_f32_16x16x32_bf16 v[60:63], v[228:231], v[182:185], v[60:63]
	s_waitcnt vmcnt(15)
	v_mfma_f32_16x16x32_bf16 v[56:59], v[232:235], v[182:185], v[56:59]
	ds_write_b128 v175, v[96:99]
	v_mfma_f32_16x16x32_bf16 v[52:55], v[236:239], v[182:185], v[52:55]
	s_waitcnt vmcnt(14)
	v_mfma_f32_16x16x32_bf16 v[48:51], v[240:243], v[182:185], v[48:51]
	ds_write_b128 v175, v[100:103] offset:16384
	v_mfma_f32_16x16x32_bf16 v[44:47], v[228:231], v[186:189], v[44:47]
	s_waitcnt vmcnt(13)
	v_mfma_f32_16x16x32_bf16 v[40:43], v[232:235], v[186:189], v[40:43]
	ds_write_b128 v175, v[104:107] offset:4096
	v_mfma_f32_16x16x32_bf16 v[36:39], v[236:239], v[186:189], v[36:39]
	s_waitcnt vmcnt(12)
	v_mfma_f32_16x16x32_bf16 v[32:35], v[240:243], v[186:189], v[32:35]
	ds_write_b128 v175, v[108:111] offset:20480
	v_mfma_f32_16x16x32_bf16 v[28:31], v[228:231], v[220:223], v[28:31]
	s_waitcnt vmcnt(11)
	v_mfma_f32_16x16x32_bf16 v[24:27], v[232:235], v[220:223], v[24:27]
	ds_write_b128 v175, v[112:115] offset:8192
	v_mfma_f32_16x16x32_bf16 v[20:23], v[236:239], v[220:223], v[20:23]
	s_waitcnt vmcnt(10)
	v_mfma_f32_16x16x32_bf16 v[16:19], v[240:243], v[220:223], v[16:19]
	ds_write_b128 v175, v[116:119] offset:24576
	v_mfma_f32_16x16x32_bf16 v[12:15], v[228:231], v[224:227], v[12:15]
	s_waitcnt vmcnt(9)
	v_mfma_f32_16x16x32_bf16 v[8:11], v[232:235], v[224:227], v[8:11]
	ds_write_b128 v175, v[120:123] offset:12288
	v_mfma_f32_16x16x32_bf16 v[4:7], v[236:239], v[224:227], v[4:7]
	s_waitcnt vmcnt(8)
	v_mfma_f32_16x16x32_bf16 v[0:3], v[240:243], v[224:227], v[0:3]
	ds_write_b128 v175, v[124:127] offset:28672
	s_waitcnt lgkmcnt(0)
	s_barrier
	ds_read_b128 v[182:185], v176
	ds_read_b128 v[186:189], v176 offset:2048
	ds_read_b128 v[220:223], v176 offset:4096
	ds_read_b128 v[224:227], v176 offset:6144
	ds_read_b128 v[228:231], v178 offset:16384
	ds_read_b128 v[232:235], v178 offset:18432
	ds_read_b128 v[236:239], v178 offset:20480
	ds_read_b128 v[240:243], v178 offset:22528
	v_mfma_f32_16x16x32_bf16 v[60:63], v[210:213], v[194:197], v[60:63]
	v_lshl_add_u64 v[120:121], v[138:139], 0, s[56:57]
	v_mfma_f32_16x16x32_bf16 v[56:59], v[214:217], v[194:197], v[56:59]
	v_add_co_u32_e32 v104, vcc, s49, v120
	v_lshl_add_u64 v[124:125], v[140:141], 0, s[56:57]
	v_mfma_f32_16x16x32_bf16 v[52:55], v[244:247], v[194:197], v[52:55]
	s_nop 0
	v_addc_co_u32_e32 v105, vcc, 0, v121, vcc
	v_mfma_f32_16x16x32_bf16 v[48:51], v[248:251], v[194:197], v[48:51]
	v_add_co_u32_e32 v108, vcc, s49, v124
	v_mfma_f32_16x16x32_bf16 v[44:47], v[210:213], v[198:201], v[44:47]
	global_load_dwordx4 v[96:99], v[120:121], off offset:512
	global_load_dwordx4 v[100:103], v[124:125], off offset:512
	v_mfma_f32_16x16x32_bf16 v[40:43], v[214:217], v[198:201], v[40:43]
	v_addc_co_u32_e32 v109, vcc, 0, v125, vcc
	v_add_co_u32_e32 v112, vcc, s50, v120
	v_mfma_f32_16x16x32_bf16 v[36:39], v[244:247], v[198:201], v[36:39]
	global_load_dwordx4 v[104:107], v[104:105], off offset:512
	v_mfma_f32_16x16x32_bf16 v[32:35], v[248:251], v[198:201], v[32:35]
	s_nop 0
	v_addc_co_u32_e32 v113, vcc, 0, v121, vcc
	v_mfma_f32_16x16x32_bf16 v[28:31], v[210:213], v[202:205], v[28:31]
	v_add_co_u32_e32 v116, vcc, s50, v124
	global_load_dwordx4 v[108:111], v[108:109], off offset:512
	v_mfma_f32_16x16x32_bf16 v[24:27], v[214:217], v[202:205], v[24:27]
	s_nop 0
	v_mfma_f32_16x16x32_bf16 v[20:23], v[244:247], v[202:205], v[20:23]
	v_addc_co_u32_e32 v117, vcc, 0, v125, vcc
	v_add_co_u32_e32 v120, vcc, s51, v120
	v_mfma_f32_16x16x32_bf16 v[16:19], v[248:251], v[202:205], v[16:19]
	global_load_dwordx4 v[112:115], v[112:113], off offset:512
	s_nop 0
	v_mfma_f32_16x16x32_bf16 v[12:15], v[210:213], v[206:209], v[12:15]
	v_addc_co_u32_e32 v121, vcc, 0, v121, vcc
	v_mfma_f32_16x16x32_bf16 v[8:11], v[214:217], v[206:209], v[8:11]
	v_add_co_u32_e32 v124, vcc, s51, v124
	global_load_dwordx4 v[116:119], v[116:117], off offset:512
	v_mfma_f32_16x16x32_bf16 v[4:7], v[244:247], v[206:209], v[4:7]
	s_nop 0
	v_addc_co_u32_e32 v125, vcc, 0, v125, vcc
	v_mfma_f32_16x16x32_bf16 v[0:3], v[248:251], v[206:209], v[0:3]
	global_load_dwordx4 v[120:123], v[120:121], off offset:512
	global_load_dwordx4 v[124:127], v[124:125], off offset:512
	s_cbranch_scc0 .Lxk_229
	s_waitcnt vmcnt(0) lgkmcnt(0)

.LBB0_262:
	v_mov_b32_e32 v194, 0x11004
	v_mov_b32_e32 v195, 1
	v_mov_b32_e32 v196, 0x3727c5ac
	v_mov_b32_e32 v197, 0x260
	v_mov_b32_e32 v198, -1
	v_mbcnt_lo_u32_b32 v199, -1, 0
	v_mbcnt_hi_u32_b32 v199, -1, v199
	v_and_b32_e32 v200, 64, v199
	v_add_u32_e32 v201, 64, v200
	v_xor_b32_e32 v202, 32, v199
	v_xor_b32_e32 v203, 16, v199
	v_xor_b32_e32 v204, 8, v199
	v_xor_b32_e32 v205, 4, v199
	v_xor_b32_e32 v206, 2, v199
	v_xor_b32_e32 v207, 1, v199
	v_mov_b32_e32 v208, 0xffffdff0
	v_mov_b32_e32 v209, 0x2000
	v_mov_b32_e32 v210, 0x8100
	v_mov_b32_e32 v211, 0x402000
	v_mov_b32_e32 v212, 8
	v_bfrev_b32_e32 v213, 0.5
	v_bfrev_b32_e32 v214, -2
	v_mov_b32_e32 v215, 0x500
	v_mov_b32_e32 v216, 0xa00
	v_mov_b32_e32 v217, 0x41b17218
	s_mov_b64 s[0:1], 0
	s_movk_i32 s14, 0x6520
	v_readlane_b32 s16, v252, 20
